# fused resid+norm epilogues (w_o, down): residual loads software-pipelined two row-groups ahead with counted vmcnt
# speedup vs baseline: 1.0099x; 1.0099x over previous
.LBB0_74:
	v_and_b32_e32 v133, 64, v193
	v_xor_b32_e32 v30, 16, v193
	v_add_u32_e32 v133, 64, v133
	s_lshl_b32 s10, s19, 8
	v_cmp_lt_i32_e32 vcc, v30, v133
	v_xor_b32_e32 v134, 32, v193
	s_add_i32 s1, s10, s27
	v_cndmask_b32_e32 v30, v193, v30, vcc
	v_cmp_lt_i32_e32 vcc, v134, v133
	s_lshl_b32 s0, s25, 5
	v_or_b32_e32 v132, s1, v144
	s_lshl_b32 s1, s6, 8
	v_cndmask_b32_e32 v133, v193, v134, vcc
	v_lshrrev_b32_e32 v28, 1, v162
	s_or_b32 s0, s1, s0
	v_lshlrev_b32_e32 v136, 2, v133
	v_ashrrev_i32_e32 v133, 31, v132
	v_readlane_b32 s12, v250, 1
	v_and_or_b32 v28, v28, 24, s0
	v_lshlrev_b64 v[134:135], 12, v[132:133]
	v_readlane_b32 s13, v250, 2
	v_ashrrev_i32_e32 v29, 31, v28
	s_barrier
	v_lshl_add_u64 v[134:135], s[12:13], 0, v[134:135]
	v_lshl_add_u64 v[164:165], v[28:29], 2, v[134:135]
	v_mov_b64_e32 v[236:237], v[164:165]
	global_load_dwordx4 v[204:207], v[236:237], off offset:16
	global_load_dwordx4 v[208:211], v[236:237], off
	global_load_dwordx4 v[212:215], v[236:237], off offset:528
	global_load_dwordx4 v[216:219], v[236:237], off offset:512
	s_mov_b64 s[60:61], 0x10000
	v_lshl_add_u64 v[238:239], v[236:237], 0, s[60:61]
	global_load_dwordx4 v[220:223], v[238:239], off offset:16
	global_load_dwordx4 v[224:227], v[238:239], off
	global_load_dwordx4 v[228:231], v[238:239], off offset:528
	global_load_dwordx4 v[232:235], v[238:239], off offset:512
	v_lshlrev_b32_e32 v30, 2, v30
	s_lshl_b32 s0, s25, 2
	s_add_i32 s2, s0, 0
	v_cmp_gt_u32_e64 s[38:39], 16, v160
	v_readlane_b32 s14, v250, 3
	v_readlane_b32 s15, v250, 4
	s_waitcnt vmcnt(6)
	v_pk_add_f32 v[58:59], v[58:59], v[206:207]
	v_pk_add_f32 v[66:67], v[66:67], v[210:211]
	v_pk_add_f32 v[64:65], v[64:65], v[208:209]
	v_pk_add_f32 v[56:57], v[56:57], v[204:205]
	v_mul_f32_e32 v134, v65, v65
	v_mul_f32_e32 v135, v67, v67
	v_fmac_f32_e32 v134, v64, v64
	v_fmac_f32_e32 v135, v66, v66
	v_add_f32_e32 v134, v134, v135
	v_mul_f32_e32 v135, v57, v57
	v_fmac_f32_e32 v135, v56, v56
	v_add_f32_e32 v134, v134, v135
	v_mul_f32_e32 v135, v59, v59
	v_fmac_f32_e32 v135, v58, v58
	v_add_f32_e32 v134, v135, v134
	s_waitcnt vmcnt(4)
	v_pk_add_f32 v[68:69], v[68:69], v[212:213]
	v_pk_add_f32 v[74:75], v[74:75], v[218:219]
	v_pk_add_f32 v[72:73], v[72:73], v[216:217]
	v_mul_f32_e32 v137, v75, v75
	v_mul_f32_e32 v135, v73, v73
	v_fmac_f32_e32 v135, v72, v72
	v_fmac_f32_e32 v137, v74, v74
	v_add_f32_e32 v135, v135, v137
	v_mul_f32_e32 v137, v69, v69
	v_pk_add_f32 v[70:71], v[70:71], v[214:215]
	s_mov_b64 s[60:61], 0x20000
	v_lshl_add_u64 v[238:239], v[236:237], 0, s[60:61]
	global_load_dwordx4 v[204:207], v[238:239], off offset:16
	global_load_dwordx4 v[208:211], v[238:239], off
	global_load_dwordx4 v[212:215], v[238:239], off offset:528
	global_load_dwordx4 v[216:219], v[238:239], off offset:512
	v_fmac_f32_e32 v137, v68, v68
	v_add_f32_e32 v135, v135, v137
	v_mul_f32_e32 v137, v71, v71
	v_fmac_f32_e32 v137, v70, v70
	v_add_f32_e32 v135, v137, v135
	v_add_f32_e32 v134, v134, v135
	ds_bpermute_b32 v135, v30, v134
	v_lshl_add_u32 v137, v201, 4, s2
	s_waitcnt lgkmcnt(0)
	v_add_f32_e32 v134, v134, v135
	ds_bpermute_b32 v135, v136, v134
	s_and_saveexec_b64 s[0:1], s[38:39]
	s_cbranch_execz .LBB0_76
	s_waitcnt lgkmcnt(0)
	v_add_f32_e32 v134, v134, v135
	ds_write_b32 v137, v134
.LBB0_76:
	s_or_b64 exec, exec, s[0:1]
	v_or_b32_e32 v134, 16, v132
	s_waitcnt lgkmcnt(0)
	v_ashrrev_i32_e32 v135, 31, v134
	v_readlane_b32 s12, v250, 1
	v_lshlrev_b64 v[134:135], 12, v[134:135]
	v_readlane_b32 s13, v250, 2
	v_readlane_b32 s14, v250, 3
	v_readlane_b32 s15, v250, 4
	v_lshl_add_u64 v[134:135], s[12:13], 0, v[134:135]
	v_lshl_add_u64 v[166:167], v[28:29], 2, v[134:135]
	s_waitcnt vmcnt(6)
	v_pk_add_f32 v[78:79], v[78:79], v[222:223]
	v_pk_add_f32 v[82:83], v[82:83], v[226:227]
	v_pk_add_f32 v[80:81], v[80:81], v[224:225]
	v_pk_add_f32 v[76:77], v[76:77], v[220:221]
	v_mul_f32_e32 v134, v81, v81
	v_mul_f32_e32 v135, v83, v83
	v_fmac_f32_e32 v134, v80, v80
	v_fmac_f32_e32 v135, v82, v82
	v_add_f32_e32 v134, v134, v135
	v_mul_f32_e32 v135, v77, v77
	v_fmac_f32_e32 v135, v76, v76
	v_add_f32_e32 v134, v134, v135
	v_mul_f32_e32 v135, v79, v79
	v_fmac_f32_e32 v135, v78, v78
	v_add_f32_e32 v134, v135, v134
	s_waitcnt vmcnt(4)
	v_pk_add_f32 v[92:93], v[92:93], v[228:229]
	v_pk_add_f32 v[98:99], v[98:99], v[234:235]
	v_pk_add_f32 v[96:97], v[96:97], v[232:233]
	v_mul_f32_e32 v138, v99, v99
	v_mul_f32_e32 v135, v97, v97
	v_fmac_f32_e32 v135, v96, v96
	v_fmac_f32_e32 v138, v98, v98
	v_add_f32_e32 v135, v135, v138
	v_mul_f32_e32 v138, v93, v93
	v_pk_add_f32 v[94:95], v[94:95], v[230:231]
	s_mov_b64 s[60:61], 0x30000
	v_lshl_add_u64 v[238:239], v[236:237], 0, s[60:61]
	global_load_dwordx4 v[220:223], v[238:239], off offset:16
	global_load_dwordx4 v[224:227], v[238:239], off
	global_load_dwordx4 v[228:231], v[238:239], off offset:528
	global_load_dwordx4 v[232:235], v[238:239], off offset:512
	v_fmac_f32_e32 v138, v92, v92
	v_add_f32_e32 v135, v135, v138
	v_mul_f32_e32 v138, v95, v95
	v_fmac_f32_e32 v138, v94, v94
	v_add_f32_e32 v135, v138, v135
	v_add_f32_e32 v134, v134, v135
	ds_bpermute_b32 v135, v30, v134
	s_waitcnt lgkmcnt(0)
	v_add_f32_e32 v134, v134, v135
	ds_bpermute_b32 v135, v136, v134
	s_and_saveexec_b64 s[0:1], s[38:39]
	s_cbranch_execz .LBB0_78
	s_waitcnt lgkmcnt(0)
	v_add_f32_e32 v134, v134, v135
	ds_write_b32 v137, v134 offset:256
.LBB0_78:
	s_or_b64 exec, exec, s[0:1]
	v_or_b32_e32 v134, 32, v132
	s_waitcnt lgkmcnt(0)
	v_ashrrev_i32_e32 v135, 31, v134
	v_readlane_b32 s12, v250, 1
	v_lshlrev_b64 v[134:135], 12, v[134:135]
	v_readlane_b32 s13, v250, 2
	v_readlane_b32 s14, v250, 3
	v_readlane_b32 s15, v250, 4
	v_lshl_add_u64 v[134:135], s[12:13], 0, v[134:135]
	v_lshl_add_u64 v[168:169], v[28:29], 2, v[134:135]
	s_waitcnt vmcnt(6)
	v_pk_add_f32 v[102:103], v[102:103], v[206:207]
	v_pk_add_f32 v[106:107], v[106:107], v[210:211]
	v_pk_add_f32 v[104:105], v[104:105], v[208:209]
	v_pk_add_f32 v[100:101], v[100:101], v[204:205]
	v_mul_f32_e32 v134, v105, v105
	v_mul_f32_e32 v135, v107, v107
	v_fmac_f32_e32 v134, v104, v104
	v_fmac_f32_e32 v135, v106, v106
	v_add_f32_e32 v134, v134, v135
	v_mul_f32_e32 v135, v101, v101
	v_fmac_f32_e32 v135, v100, v100
	v_add_f32_e32 v134, v134, v135
	v_mul_f32_e32 v135, v103, v103
	v_fmac_f32_e32 v135, v102, v102
	v_add_f32_e32 v134, v135, v134
	s_waitcnt vmcnt(4)
	v_pk_add_f32 v[108:109], v[108:109], v[212:213]
	v_pk_add_f32 v[114:115], v[114:115], v[218:219]
	v_pk_add_f32 v[112:113], v[112:113], v[216:217]
	v_mul_f32_e32 v138, v115, v115
	v_mul_f32_e32 v135, v113, v113
	v_fmac_f32_e32 v135, v112, v112
	v_fmac_f32_e32 v138, v114, v114
	v_add_f32_e32 v135, v135, v138
	v_mul_f32_e32 v138, v109, v109
	v_pk_add_f32 v[110:111], v[110:111], v[214:215]
	s_mov_b64 s[60:61], 0x80000
	v_lshl_add_u64 v[238:239], v[236:237], 0, s[60:61]
	global_load_dwordx4 v[204:207], v[238:239], off offset:16
	global_load_dwordx4 v[208:211], v[238:239], off
	global_load_dwordx4 v[212:215], v[238:239], off offset:528
	global_load_dwordx4 v[216:219], v[238:239], off offset:512
	v_fmac_f32_e32 v138, v108, v108
	v_add_f32_e32 v135, v135, v138
	v_mul_f32_e32 v138, v111, v111
	v_fmac_f32_e32 v138, v110, v110
	v_add_f32_e32 v135, v138, v135
	v_add_f32_e32 v134, v134, v135
	ds_bpermute_b32 v135, v30, v134
	s_waitcnt lgkmcnt(0)
	v_add_f32_e32 v134, v134, v135
	ds_bpermute_b32 v135, v136, v134
	s_and_saveexec_b64 s[0:1], s[38:39]
	s_cbranch_execz .LBB0_80
	s_waitcnt lgkmcnt(0)
	v_add_f32_e32 v134, v134, v135
	ds_write_b32 v137, v134 offset:512
.LBB0_80:
	s_or_b64 exec, exec, s[0:1]
	v_or_b32_e32 v134, 48, v132
	s_waitcnt lgkmcnt(0)
	v_ashrrev_i32_e32 v135, 31, v134
	v_readlane_b32 s12, v250, 1
	v_lshlrev_b64 v[134:135], 12, v[134:135]
	v_readlane_b32 s13, v250, 2
	v_readlane_b32 s14, v250, 3
	v_readlane_b32 s15, v250, 4
	v_lshl_add_u64 v[134:135], s[12:13], 0, v[134:135]
	v_lshl_add_u64 v[170:171], v[28:29], 2, v[134:135]
	s_waitcnt vmcnt(6)
	v_pk_add_f32 v[118:119], v[118:119], v[222:223]
	v_pk_add_f32 v[122:123], v[122:123], v[226:227]
	v_pk_add_f32 v[120:121], v[120:121], v[224:225]
	v_pk_add_f32 v[116:117], v[116:117], v[220:221]
	v_mul_f32_e32 v134, v121, v121
	v_mul_f32_e32 v135, v123, v123
	v_fmac_f32_e32 v134, v120, v120
	v_fmac_f32_e32 v135, v122, v122
	v_add_f32_e32 v134, v134, v135
	v_mul_f32_e32 v135, v117, v117
	v_fmac_f32_e32 v135, v116, v116
	v_add_f32_e32 v134, v134, v135
	v_mul_f32_e32 v135, v119, v119
	v_fmac_f32_e32 v135, v118, v118
	v_add_f32_e32 v134, v135, v134
	s_waitcnt vmcnt(4)
	v_pk_add_f32 v[124:125], v[124:125], v[228:229]
	v_pk_add_f32 v[130:131], v[130:131], v[234:235]
	v_pk_add_f32 v[128:129], v[128:129], v[232:233]
	v_mul_f32_e32 v138, v131, v131
	v_mul_f32_e32 v135, v129, v129
	v_fmac_f32_e32 v135, v128, v128
	v_fmac_f32_e32 v138, v130, v130
	v_add_f32_e32 v135, v135, v138
	v_mul_f32_e32 v138, v125, v125
	v_pk_add_f32 v[126:127], v[126:127], v[230:231]
	s_mov_b64 s[60:61], 0x90000
	v_lshl_add_u64 v[238:239], v[236:237], 0, s[60:61]
	global_load_dwordx4 v[220:223], v[238:239], off offset:16
	global_load_dwordx4 v[224:227], v[238:239], off
	global_load_dwordx4 v[228:231], v[238:239], off offset:528
	global_load_dwordx4 v[232:235], v[238:239], off offset:512
	v_fmac_f32_e32 v138, v124, v124
	v_add_f32_e32 v135, v135, v138
	v_mul_f32_e32 v138, v127, v127
	v_fmac_f32_e32 v138, v126, v126
	v_add_f32_e32 v135, v138, v135
	v_add_f32_e32 v134, v134, v135
	ds_bpermute_b32 v135, v30, v134
	s_waitcnt lgkmcnt(0)
	v_add_f32_e32 v134, v134, v135
	ds_bpermute_b32 v135, v136, v134
	s_and_saveexec_b64 s[0:1], s[38:39]
	s_cbranch_execz .LBB0_82
	s_waitcnt lgkmcnt(0)
	v_add_f32_e32 v134, v134, v135
	ds_write_b32 v137, v134 offset:768
.LBB0_82:
	s_or_b64 exec, exec, s[0:1]
	v_readlane_b32 s12, v250, 1
	s_waitcnt lgkmcnt(0)
	v_lshlrev_b64 v[134:135], 12, v[132:133]
	v_readlane_b32 s13, v250, 2
	s_mov_b64 s[0:1], 0x80000
	v_add_u32_e32 v202, 0x80, v201
	v_lshl_add_u64 v[134:135], s[12:13], 0, v[134:135]
	v_lshl_add_u64 v[134:135], v[28:29], 2, v[134:135]
	v_add_co_u32_e32 v138, vcc, 0x80000, v134
	v_lshl_add_u64 v[172:173], v[134:135], 0, s[0:1]
	s_nop 0
	v_addc_co_u32_e32 v139, vcc, 0, v135, vcc
	s_nop 0
	v_readlane_b32 s14, v250, 3
	v_readlane_b32 s15, v250, 4
	s_waitcnt vmcnt(6)
	v_pk_add_f32 v[90:91], v[90:91], v[210:211]
	v_pk_add_f32 v[88:89], v[88:89], v[208:209]
	v_mul_f32_e32 v139, v91, v91
	v_mul_f32_e32 v138, v89, v89
	v_pk_add_f32 v[84:85], v[84:85], v[204:205]
	v_fmac_f32_e32 v138, v88, v88
	v_fmac_f32_e32 v139, v90, v90
	v_add_f32_e32 v138, v138, v139
	v_mul_f32_e32 v139, v85, v85
	v_pk_add_f32 v[86:87], v[86:87], v[206:207]
	v_fmac_f32_e32 v139, v84, v84
	v_add_f32_e32 v138, v138, v139
	v_mul_f32_e32 v139, v87, v87
	v_fmac_f32_e32 v139, v86, v86
	v_add_f32_e32 v146, v139, v138
	s_waitcnt vmcnt(4)
	v_pk_add_f32 v[52:53], v[52:53], v[212:213]
	v_pk_add_f32 v[62:63], v[62:63], v[218:219]
	v_pk_add_f32 v[60:61], v[60:61], v[216:217]
	v_mul_f32_e32 v139, v63, v63
	v_mul_f32_e32 v138, v61, v61
	v_fmac_f32_e32 v138, v60, v60
	v_fmac_f32_e32 v139, v62, v62
	v_add_f32_e32 v138, v138, v139
	v_mul_f32_e32 v139, v53, v53
	v_pk_add_f32 v[54:55], v[54:55], v[214:215]
	s_mov_b64 s[60:61], 0xa0000
	v_lshl_add_u64 v[238:239], v[236:237], 0, s[60:61]
	global_load_dwordx4 v[204:207], v[238:239], off offset:16
	global_load_dwordx4 v[208:211], v[238:239], off
	global_load_dwordx4 v[212:215], v[238:239], off offset:528
	global_load_dwordx4 v[216:219], v[238:239], off offset:512
	v_fmac_f32_e32 v139, v52, v52
	v_add_f32_e32 v138, v138, v139
	v_mul_f32_e32 v139, v55, v55
	v_fmac_f32_e32 v139, v54, v54
	v_add_f32_e32 v138, v139, v138
	v_add_f32_e32 v138, v146, v138
	ds_bpermute_b32 v139, v30, v138
	s_waitcnt lgkmcnt(0)
	v_add_f32_e32 v138, v138, v139
	ds_bpermute_b32 v139, v136, v138
	s_and_saveexec_b64 s[0:1], s[38:39]
	s_cbranch_execz .LBB0_84
	v_lshl_add_u32 v140, v202, 4, s2
	s_waitcnt lgkmcnt(0)
	v_add_f32_e32 v138, v138, v139
	ds_write_b32 v140, v138
.LBB0_84:
	s_or_b64 exec, exec, s[0:1]
	s_mov_b64 s[0:1], 0x90000
	v_lshl_add_u64 v[174:175], v[134:135], 0, s[0:1]
	v_add_co_u32_e32 v134, vcc, 0x90000, v134
	s_nop 1
	v_addc_co_u32_e32 v135, vcc, 0, v135, vcc
	s_waitcnt lgkmcnt(0)
	s_waitcnt vmcnt(6)
	v_pk_add_f32 v[50:51], v[50:51], v[226:227]
	v_pk_add_f32 v[48:49], v[48:49], v[224:225]
	v_pk_add_f32 v[46:47], v[46:47], v[222:223]
	v_pk_add_f32 v[44:45], v[44:45], v[220:221]
	v_mul_f32_e32 v134, v49, v49
	v_mul_f32_e32 v135, v51, v51
	v_fmac_f32_e32 v134, v48, v48
	v_fmac_f32_e32 v135, v50, v50
	v_add_f32_e32 v134, v134, v135
	v_mul_f32_e32 v135, v45, v45
	v_fmac_f32_e32 v135, v44, v44
	v_add_f32_e32 v134, v134, v135
	v_mul_f32_e32 v135, v47, v47
	v_fmac_f32_e32 v135, v46, v46
	v_add_f32_e32 v134, v135, v134
	s_waitcnt vmcnt(4)
	v_pk_add_f32 v[36:37], v[36:37], v[228:229]
	v_pk_add_f32 v[42:43], v[42:43], v[234:235]
	v_pk_add_f32 v[40:41], v[40:41], v[232:233]
	v_mul_f32_e32 v138, v43, v43
	v_mul_f32_e32 v135, v41, v41
	v_fmac_f32_e32 v135, v40, v40
	v_fmac_f32_e32 v138, v42, v42
	v_add_f32_e32 v135, v135, v138
	v_mul_f32_e32 v138, v37, v37
	v_pk_add_f32 v[38:39], v[38:39], v[230:231]
	s_mov_b64 s[60:61], 0xb0000
	v_lshl_add_u64 v[238:239], v[236:237], 0, s[60:61]
	global_load_dwordx4 v[220:223], v[238:239], off offset:16
	global_load_dwordx4 v[224:227], v[238:239], off
	global_load_dwordx4 v[228:231], v[238:239], off offset:528
	global_load_dwordx4 v[232:235], v[238:239], off offset:512
	v_fmac_f32_e32 v138, v36, v36
	v_add_f32_e32 v135, v135, v138
	v_mul_f32_e32 v138, v39, v39
	v_fmac_f32_e32 v138, v38, v38
	v_add_f32_e32 v135, v138, v135
	v_add_f32_e32 v134, v134, v135
	ds_bpermute_b32 v135, v30, v134
	s_waitcnt lgkmcnt(0)
	v_add_f32_e32 v134, v134, v135
	ds_bpermute_b32 v135, v136, v134
	s_and_saveexec_b64 s[0:1], s[38:39]
	s_cbranch_execz .LBB0_86
	s_waitcnt lgkmcnt(0)
	v_add_f32_e32 v134, v134, v135
	ds_write_b32 v137, v134 offset:2304
.LBB0_86:
	s_or_b64 exec, exec, s[0:1]
	v_readlane_b32 s0, v250, 1
	v_lshlrev_b64 v[132:133], 12, v[132:133]
	v_readlane_b32 s1, v250, 2
	v_readlane_b32 s2, v250, 3
	v_readlane_b32 s3, v250, 4
	v_lshl_add_u64 v[132:133], s[0:1], 0, v[132:133]
	v_lshl_add_u64 v[132:133], v[28:29], 2, v[132:133]
	v_add_co_u32_e32 v134, vcc, 0xa0000, v132
	s_mov_b64 s[0:1], 0xa0000
	s_waitcnt lgkmcnt(0)
	v_addc_co_u32_e32 v135, vcc, 0, v133, vcc
	v_lshl_add_u64 v[176:177], v[132:133], 0, s[0:1]
	s_waitcnt vmcnt(6)
	v_pk_add_f32 v[34:35], v[34:35], v[210:211]
	v_pk_add_f32 v[32:33], v[32:33], v[208:209]
	v_pk_add_f32 v[26:27], v[26:27], v[206:207]
	v_pk_add_f32 v[24:25], v[24:25], v[204:205]
	v_mul_f32_e32 v134, v33, v33
	v_mul_f32_e32 v135, v35, v35
	v_fmac_f32_e32 v134, v32, v32
	v_fmac_f32_e32 v135, v34, v34
	v_add_f32_e32 v134, v134, v135
	v_mul_f32_e32 v135, v25, v25
	v_fmac_f32_e32 v135, v24, v24
	v_add_f32_e32 v134, v134, v135
	v_mul_f32_e32 v135, v27, v27
	v_fmac_f32_e32 v135, v26, v26
	v_add_f32_e32 v134, v135, v134
	s_waitcnt vmcnt(4)
	v_pk_add_f32 v[16:17], v[16:17], v[212:213]
	v_pk_add_f32 v[22:23], v[22:23], v[218:219]
	v_pk_add_f32 v[20:21], v[20:21], v[216:217]
	v_mul_f32_e32 v138, v23, v23
	v_mul_f32_e32 v135, v21, v21
	v_fmac_f32_e32 v135, v20, v20
	v_fmac_f32_e32 v138, v22, v22
	v_add_f32_e32 v135, v135, v138
	v_mul_f32_e32 v138, v17, v17
	v_pk_add_f32 v[18:19], v[18:19], v[214:215]
	v_fmac_f32_e32 v138, v16, v16
	v_add_f32_e32 v135, v135, v138
	v_mul_f32_e32 v138, v19, v19
	v_fmac_f32_e32 v138, v18, v18
	v_add_f32_e32 v135, v138, v135
	v_add_f32_e32 v134, v134, v135
	ds_bpermute_b32 v135, v30, v134
	s_waitcnt lgkmcnt(0)
	v_add_f32_e32 v134, v134, v135
	ds_bpermute_b32 v135, v136, v134
	s_and_saveexec_b64 s[0:1], s[38:39]
	s_cbranch_execz .LBB0_88
	s_waitcnt lgkmcnt(0)
	v_add_f32_e32 v134, v134, v135
	ds_write_b32 v137, v134 offset:2560
.LBB0_88:
	s_or_b64 exec, exec, s[0:1]
	s_mov_b64 s[0:1], 0xb0000
	v_lshl_add_u64 v[178:179], v[132:133], 0, s[0:1]
	v_add_co_u32_e32 v132, vcc, 0xb0000, v132
	s_nop 1
	v_addc_co_u32_e32 v133, vcc, 0, v133, vcc
	s_waitcnt lgkmcnt(0)
	s_nop 0
	s_waitcnt vmcnt(2)
	v_pk_add_f32 v[14:15], v[14:15], v[226:227]
	v_pk_add_f32 v[12:13], v[12:13], v[224:225]
	v_mul_f32_e32 v133, v15, v15
	v_mul_f32_e32 v132, v13, v13
	v_pk_add_f32 v[8:9], v[8:9], v[220:221]
	v_fmac_f32_e32 v132, v12, v12
	v_fmac_f32_e32 v133, v14, v14
	v_add_f32_e32 v132, v132, v133
	v_mul_f32_e32 v133, v9, v9
	v_pk_add_f32 v[10:11], v[10:11], v[222:223]
	v_fmac_f32_e32 v133, v8, v8
	v_add_f32_e32 v132, v132, v133
	v_mul_f32_e32 v133, v11, v11
	v_fmac_f32_e32 v133, v10, v10
	v_add_f32_e32 v142, v133, v132
	s_waitcnt vmcnt(0)
	v_pk_add_f32 v[0:1], v[0:1], v[228:229]
	v_pk_add_f32 v[6:7], v[6:7], v[234:235]
	v_pk_add_f32 v[4:5], v[4:5], v[232:233]
	v_mul_f32_e32 v133, v7, v7
	v_mul_f32_e32 v132, v5, v5
	v_fmac_f32_e32 v132, v4, v4
	v_fmac_f32_e32 v133, v6, v6
	v_add_f32_e32 v132, v132, v133
	v_mul_f32_e32 v133, v1, v1
	v_pk_add_f32 v[2:3], v[2:3], v[230:231]
	v_fmac_f32_e32 v133, v0, v0
	v_add_f32_e32 v132, v132, v133
	v_mul_f32_e32 v133, v3, v3
	v_fmac_f32_e32 v133, v2, v2
	v_add_f32_e32 v132, v133, v132
	v_add_f32_e32 v132, v142, v132
	ds_bpermute_b32 v30, v30, v132
	s_waitcnt lgkmcnt(0)
	v_add_f32_e32 v30, v132, v30
	ds_bpermute_b32 v132, v136, v30
	s_and_saveexec_b64 s[0:1], s[38:39]
	s_cbranch_execz .LBB0_90
	s_waitcnt lgkmcnt(0)
	v_add_f32_e32 v30, v30, v132
	ds_write_b32 v137, v30 offset:2816

.LBB0_330:
	v_and_b32_e32 v133, 64, v193
	v_xor_b32_e32 v30, 16, v193
	v_add_u32_e32 v133, 64, v133
	s_lshl_b32 s8, s23, 8
	v_cmp_lt_i32_e32 vcc, v30, v133
	v_xor_b32_e32 v134, 32, v193
	s_add_i32 s1, s8, s31
	v_cndmask_b32_e32 v30, v193, v30, vcc
	v_cmp_lt_i32_e32 vcc, v134, v133
	s_lshl_b32 s0, s29, 5
	v_or_b32_e32 v132, s1, v144
	s_lshl_b32 s1, s12, 8
	v_cndmask_b32_e32 v133, v193, v134, vcc
	v_lshrrev_b32_e32 v28, 1, v162
	s_or_b32 s0, s1, s0
	v_lshlrev_b32_e32 v136, 2, v133
	v_ashrrev_i32_e32 v133, 31, v132
	v_and_or_b32 v28, v28, 24, s0
	v_lshlrev_b64 v[134:135], 12, v[132:133]
	v_ashrrev_i32_e32 v29, 31, v28
	v_lshl_add_u64 v[134:135], s[6:7], 0, v[134:135]
	v_lshl_add_u64 v[134:135], v[28:29], 2, v[134:135]
	s_barrier
	v_mov_b64_e32 v[236:237], v[134:135]
	global_load_dwordx4 v[204:207], v[236:237], off offset:16
	global_load_dwordx4 v[208:211], v[236:237], off
	global_load_dwordx4 v[212:215], v[236:237], off offset:528
	global_load_dwordx4 v[216:219], v[236:237], off offset:512
	s_mov_b64 s[60:61], 0x10000
	v_lshl_add_u64 v[238:239], v[236:237], 0, s[60:61]
	global_load_dwordx4 v[220:223], v[238:239], off offset:16
	global_load_dwordx4 v[224:227], v[238:239], off
	global_load_dwordx4 v[228:231], v[238:239], off offset:528
	global_load_dwordx4 v[232:235], v[238:239], off offset:512
	v_lshlrev_b32_e32 v30, 2, v30
	s_lshl_b32 s0, s29, 2
	s_add_i32 s2, s0, 0
	v_cmp_gt_u32_e64 s[38:39], 16, v160
	s_waitcnt vmcnt(6)
	v_pk_add_f32 v[64:65], v[64:65], v[204:205]
	v_pk_add_f32 v[58:59], v[58:59], v[210:211]
	v_pk_add_f32 v[56:57], v[56:57], v[208:209]
	v_mul_f32_e32 v138, v59, v59
	v_mul_f32_e32 v137, v57, v57
	v_fmac_f32_e32 v137, v56, v56
	v_fmac_f32_e32 v138, v58, v58
	v_add_f32_e32 v137, v137, v138
	v_mul_f32_e32 v138, v65, v65
	v_pk_add_f32 v[66:67], v[66:67], v[206:207]
	v_fmac_f32_e32 v138, v64, v64
	v_add_f32_e32 v137, v137, v138
	v_mul_f32_e32 v138, v67, v67
	v_fmac_f32_e32 v138, v66, v66
	v_add_f32_e32 v137, v138, v137
	s_waitcnt vmcnt(4)
	v_pk_add_f32 v[72:73], v[72:73], v[212:213]
	v_pk_add_f32 v[70:71], v[70:71], v[218:219]
	v_pk_add_f32 v[68:69], v[68:69], v[216:217]
	v_mul_f32_e32 v135, v71, v71
	v_mul_f32_e32 v134, v69, v69
	v_fmac_f32_e32 v134, v68, v68
	v_fmac_f32_e32 v135, v70, v70
	v_add_f32_e32 v134, v134, v135
	v_mul_f32_e32 v135, v73, v73
	v_pk_add_f32 v[74:75], v[74:75], v[214:215]
	s_mov_b64 s[60:61], 0x20000
	v_lshl_add_u64 v[238:239], v[236:237], 0, s[60:61]
	global_load_dwordx4 v[204:207], v[238:239], off offset:16
	global_load_dwordx4 v[208:211], v[238:239], off
	global_load_dwordx4 v[212:215], v[238:239], off offset:528
	global_load_dwordx4 v[216:219], v[238:239], off offset:512
	v_fmac_f32_e32 v135, v72, v72
	v_add_f32_e32 v134, v134, v135
	v_mul_f32_e32 v135, v75, v75
	v_fmac_f32_e32 v135, v74, v74
	v_add_f32_e32 v134, v135, v134
	v_add_f32_e32 v134, v137, v134
	ds_bpermute_b32 v135, v30, v134
	v_lshl_add_u32 v137, v170, 4, s2
	s_waitcnt lgkmcnt(0)
	v_add_f32_e32 v134, v134, v135
	ds_bpermute_b32 v135, v136, v134
	s_and_saveexec_b64 s[0:1], s[38:39]
	v_readlane_b32 s34, v254, 58
	v_readlane_b32 s35, v254, 59
	s_cbranch_execz .LBB0_332
	s_waitcnt lgkmcnt(0)
	v_add_f32_e32 v134, v134, v135
	ds_write_b32 v137, v134
.LBB0_332:
	s_or_b64 exec, exec, s[0:1]
	v_or_b32_e32 v134, 16, v132
	s_waitcnt lgkmcnt(0)
	v_ashrrev_i32_e32 v135, 31, v134
	v_lshlrev_b64 v[134:135], 12, v[134:135]
	v_lshl_add_u64 v[134:135], s[6:7], 0, v[134:135]
	v_lshl_add_u64 v[134:135], v[28:29], 2, v[134:135]
	s_waitcnt vmcnt(6)
	v_pk_add_f32 v[88:89], v[88:89], v[220:221]
	v_pk_add_f32 v[86:87], v[86:87], v[226:227]
	v_pk_add_f32 v[84:85], v[84:85], v[224:225]
	v_mul_f32_e32 v139, v87, v87
	v_mul_f32_e32 v138, v85, v85
	v_fmac_f32_e32 v138, v84, v84
	v_fmac_f32_e32 v139, v86, v86
	v_add_f32_e32 v138, v138, v139
	v_mul_f32_e32 v139, v89, v89
	v_pk_add_f32 v[90:91], v[90:91], v[222:223]
	v_fmac_f32_e32 v139, v88, v88
	v_add_f32_e32 v138, v138, v139
	v_mul_f32_e32 v139, v91, v91
	v_fmac_f32_e32 v139, v90, v90
	v_add_f32_e32 v146, v139, v138
	s_waitcnt vmcnt(4)
	v_pk_add_f32 v[96:97], v[96:97], v[228:229]
	v_pk_add_f32 v[94:95], v[94:95], v[234:235]
	v_pk_add_f32 v[92:93], v[92:93], v[232:233]
	v_mul_f32_e32 v135, v95, v95
	v_mul_f32_e32 v134, v93, v93
	v_fmac_f32_e32 v134, v92, v92
	v_fmac_f32_e32 v135, v94, v94
	v_add_f32_e32 v134, v134, v135
	v_mul_f32_e32 v135, v97, v97
	v_pk_add_f32 v[98:99], v[98:99], v[230:231]
	s_mov_b64 s[60:61], 0x30000
	v_lshl_add_u64 v[238:239], v[236:237], 0, s[60:61]
	global_load_dwordx4 v[220:223], v[238:239], off offset:16
	global_load_dwordx4 v[224:227], v[238:239], off
	global_load_dwordx4 v[228:231], v[238:239], off offset:528
	global_load_dwordx4 v[232:235], v[238:239], off offset:512
	v_fmac_f32_e32 v135, v96, v96
	v_add_f32_e32 v134, v134, v135
	v_mul_f32_e32 v135, v99, v99
	v_fmac_f32_e32 v135, v98, v98
	v_add_f32_e32 v134, v135, v134
	v_add_f32_e32 v134, v146, v134
	ds_bpermute_b32 v135, v30, v134
	s_waitcnt lgkmcnt(0)
	v_add_f32_e32 v134, v134, v135
	ds_bpermute_b32 v135, v136, v134
	s_and_saveexec_b64 s[0:1], s[38:39]
	s_cbranch_execz .LBB0_334
	s_waitcnt lgkmcnt(0)
	v_add_f32_e32 v134, v134, v135
	ds_write_b32 v137, v134 offset:256
.LBB0_334:
	s_or_b64 exec, exec, s[0:1]
	v_or_b32_e32 v134, 32, v132
	s_waitcnt lgkmcnt(0)
	v_ashrrev_i32_e32 v135, 31, v134
	v_lshlrev_b64 v[134:135], 12, v[134:135]
	v_lshl_add_u64 v[134:135], s[6:7], 0, v[134:135]
	v_lshl_add_u64 v[134:135], v[28:29], 2, v[134:135]
	s_waitcnt vmcnt(6)
	v_pk_add_f32 v[104:105], v[104:105], v[204:205]
	v_pk_add_f32 v[102:103], v[102:103], v[210:211]
	v_pk_add_f32 v[100:101], v[100:101], v[208:209]
	v_mul_f32_e32 v139, v103, v103
	v_mul_f32_e32 v138, v101, v101
	v_fmac_f32_e32 v138, v100, v100
	v_fmac_f32_e32 v139, v102, v102
	v_add_f32_e32 v138, v138, v139
	v_mul_f32_e32 v139, v105, v105
	v_pk_add_f32 v[106:107], v[106:107], v[206:207]
	v_fmac_f32_e32 v139, v104, v104
	v_add_f32_e32 v138, v138, v139
	v_mul_f32_e32 v139, v107, v107
	v_fmac_f32_e32 v139, v106, v106
	v_add_f32_e32 v146, v139, v138
	s_waitcnt vmcnt(4)
	v_pk_add_f32 v[120:121], v[120:121], v[212:213]
	v_pk_add_f32 v[118:119], v[118:119], v[218:219]
	v_pk_add_f32 v[116:117], v[116:117], v[216:217]
	v_mul_f32_e32 v135, v119, v119
	v_mul_f32_e32 v134, v117, v117
	v_fmac_f32_e32 v134, v116, v116
	v_fmac_f32_e32 v135, v118, v118
	v_add_f32_e32 v134, v134, v135
	v_mul_f32_e32 v135, v121, v121
	v_pk_add_f32 v[122:123], v[122:123], v[214:215]
	s_mov_b64 s[60:61], 0x80000
	v_lshl_add_u64 v[238:239], v[236:237], 0, s[60:61]
	global_load_dwordx4 v[204:207], v[238:239], off offset:16
	global_load_dwordx4 v[208:211], v[238:239], off
	global_load_dwordx4 v[212:215], v[238:239], off offset:528
	global_load_dwordx4 v[216:219], v[238:239], off offset:512
	v_fmac_f32_e32 v135, v120, v120
	v_add_f32_e32 v134, v134, v135
	v_mul_f32_e32 v135, v123, v123
	v_fmac_f32_e32 v135, v122, v122
	v_add_f32_e32 v134, v135, v134
	v_add_f32_e32 v134, v146, v134
	ds_bpermute_b32 v135, v30, v134
	s_waitcnt lgkmcnt(0)
	v_add_f32_e32 v134, v134, v135
	ds_bpermute_b32 v135, v136, v134
	s_and_saveexec_b64 s[0:1], s[38:39]
	s_cbranch_execz .LBB0_336
	s_waitcnt lgkmcnt(0)
	v_add_f32_e32 v134, v134, v135
	ds_write_b32 v137, v134 offset:512
.LBB0_336:
	s_or_b64 exec, exec, s[0:1]
	v_or_b32_e32 v134, 48, v132
	s_waitcnt lgkmcnt(0)
	v_ashrrev_i32_e32 v135, 31, v134
	v_lshlrev_b64 v[134:135], 12, v[134:135]
	v_lshl_add_u64 v[134:135], s[6:7], 0, v[134:135]
	v_lshl_add_u64 v[134:135], v[28:29], 2, v[134:135]
	s_waitcnt vmcnt(6)
	v_pk_add_f32 v[128:129], v[128:129], v[220:221]
	v_pk_add_f32 v[126:127], v[126:127], v[226:227]
	v_pk_add_f32 v[124:125], v[124:125], v[224:225]
	v_mul_f32_e32 v139, v127, v127
	v_mul_f32_e32 v138, v125, v125
	v_fmac_f32_e32 v138, v124, v124
	v_fmac_f32_e32 v139, v126, v126
	v_add_f32_e32 v138, v138, v139
	v_mul_f32_e32 v139, v129, v129
	v_pk_add_f32 v[130:131], v[130:131], v[222:223]
	v_fmac_f32_e32 v139, v128, v128
	v_add_f32_e32 v138, v138, v139
	v_mul_f32_e32 v139, v131, v131
	v_fmac_f32_e32 v139, v130, v130
	v_add_f32_e32 v146, v139, v138
	s_waitcnt vmcnt(4)
	v_pk_add_f32 v[108:109], v[108:109], v[228:229]
	v_pk_add_f32 v[114:115], v[114:115], v[234:235]
	v_pk_add_f32 v[112:113], v[112:113], v[232:233]
	v_mul_f32_e32 v135, v115, v115
	v_mul_f32_e32 v134, v113, v113
	v_fmac_f32_e32 v134, v112, v112
	v_fmac_f32_e32 v135, v114, v114
	v_add_f32_e32 v134, v134, v135
	v_mul_f32_e32 v135, v109, v109
	v_pk_add_f32 v[110:111], v[110:111], v[230:231]
	s_mov_b64 s[60:61], 0x90000
	v_lshl_add_u64 v[238:239], v[236:237], 0, s[60:61]
	global_load_dwordx4 v[220:223], v[238:239], off offset:16
	global_load_dwordx4 v[224:227], v[238:239], off
	global_load_dwordx4 v[228:231], v[238:239], off offset:528
	global_load_dwordx4 v[232:235], v[238:239], off offset:512
	v_fmac_f32_e32 v135, v108, v108
	v_add_f32_e32 v134, v134, v135
	v_mul_f32_e32 v135, v111, v111
	v_fmac_f32_e32 v135, v110, v110
	v_add_f32_e32 v134, v135, v134
	v_add_f32_e32 v134, v146, v134
	ds_bpermute_b32 v135, v30, v134
	s_waitcnt lgkmcnt(0)
	v_add_f32_e32 v134, v134, v135
	ds_bpermute_b32 v135, v136, v134
	s_and_saveexec_b64 s[0:1], s[38:39]
	s_cbranch_execz .LBB0_338
	s_waitcnt lgkmcnt(0)
	v_add_f32_e32 v134, v134, v135
	ds_write_b32 v137, v134 offset:768
.LBB0_338:
	s_or_b64 exec, exec, s[0:1]
	s_waitcnt lgkmcnt(0)
	v_lshlrev_b64 v[134:135], 12, v[132:133]
	v_lshl_add_u64 v[134:135], s[6:7], 0, v[134:135]
	v_lshl_add_u64 v[134:135], v[28:29], 2, v[134:135]
	v_add_co_u32_e32 v138, vcc, 0x80000, v134
	s_mov_b64 s[0:1], 0x80000
	s_nop 0
	v_addc_co_u32_e32 v139, vcc, 0, v135, vcc
	v_lshl_add_u64 v[146:147], v[134:135], 0, s[0:1]
	s_nop 0
	v_add_u32_e32 v171, 0x80, v170
	s_waitcnt vmcnt(6)
	v_pk_add_f32 v[82:83], v[82:83], v[210:211]
	v_pk_add_f32 v[80:81], v[80:81], v[208:209]
	v_mul_f32_e32 v139, v83, v83
	v_mul_f32_e32 v138, v81, v81
	v_pk_add_f32 v[76:77], v[76:77], v[204:205]
	v_fmac_f32_e32 v138, v80, v80
	v_fmac_f32_e32 v139, v82, v82
	v_add_f32_e32 v138, v138, v139
	v_mul_f32_e32 v139, v77, v77
	v_pk_add_f32 v[78:79], v[78:79], v[206:207]
	v_fmac_f32_e32 v139, v76, v76
	v_add_f32_e32 v138, v138, v139
	v_mul_f32_e32 v139, v79, v79
	v_fmac_f32_e32 v139, v78, v78
	v_add_f32_e32 v156, v139, v138
	s_waitcnt vmcnt(4)
	v_pk_add_f32 v[52:53], v[52:53], v[212:213]
	v_pk_add_f32 v[62:63], v[62:63], v[218:219]
	v_pk_add_f32 v[60:61], v[60:61], v[216:217]
	v_mul_f32_e32 v139, v63, v63
	v_mul_f32_e32 v138, v61, v61
	v_fmac_f32_e32 v138, v60, v60
	v_fmac_f32_e32 v139, v62, v62
	v_add_f32_e32 v138, v138, v139
	v_mul_f32_e32 v139, v53, v53
	v_pk_add_f32 v[54:55], v[54:55], v[214:215]
	s_mov_b64 s[60:61], 0xa0000
	v_lshl_add_u64 v[238:239], v[236:237], 0, s[60:61]
	global_load_dwordx4 v[204:207], v[238:239], off offset:16
	global_load_dwordx4 v[208:211], v[238:239], off
	global_load_dwordx4 v[212:215], v[238:239], off offset:528
	global_load_dwordx4 v[216:219], v[238:239], off offset:512
	v_fmac_f32_e32 v139, v52, v52
	v_add_f32_e32 v138, v138, v139
	v_mul_f32_e32 v139, v55, v55
	v_fmac_f32_e32 v139, v54, v54
	v_add_f32_e32 v138, v139, v138
	v_add_f32_e32 v138, v156, v138
	ds_bpermute_b32 v139, v30, v138
	s_waitcnt lgkmcnt(0)
	v_add_f32_e32 v138, v138, v139
	ds_bpermute_b32 v139, v136, v138
	s_and_saveexec_b64 s[0:1], s[38:39]
	s_cbranch_execz .LBB0_340
	v_lshl_add_u32 v140, v171, 4, s2
	s_waitcnt lgkmcnt(0)
	v_add_f32_e32 v138, v138, v139
	ds_write_b32 v140, v138
.LBB0_340:
	s_or_b64 exec, exec, s[0:1]
	s_mov_b64 s[0:1], 0x90000
	v_lshl_add_u64 v[146:147], v[134:135], 0, s[0:1]
	v_add_co_u32_e32 v134, vcc, 0x90000, v134
	s_nop 1
	v_addc_co_u32_e32 v135, vcc, 0, v135, vcc
	s_waitcnt lgkmcnt(0)
	s_waitcnt vmcnt(6)
	v_pk_add_f32 v[50:51], v[50:51], v[226:227]
	v_pk_add_f32 v[48:49], v[48:49], v[224:225]
	v_pk_add_f32 v[46:47], v[46:47], v[222:223]
	v_pk_add_f32 v[44:45], v[44:45], v[220:221]
	v_mul_f32_e32 v134, v49, v49
	v_mul_f32_e32 v135, v51, v51
	v_fmac_f32_e32 v134, v48, v48
	v_fmac_f32_e32 v135, v50, v50
	v_add_f32_e32 v134, v134, v135
	v_mul_f32_e32 v135, v45, v45
	v_fmac_f32_e32 v135, v44, v44
	v_add_f32_e32 v134, v134, v135
	v_mul_f32_e32 v135, v47, v47
	v_fmac_f32_e32 v135, v46, v46
	v_add_f32_e32 v134, v135, v134
	s_waitcnt vmcnt(4)
	v_pk_add_f32 v[36:37], v[36:37], v[228:229]
	v_pk_add_f32 v[42:43], v[42:43], v[234:235]
	v_pk_add_f32 v[40:41], v[40:41], v[232:233]
	v_mul_f32_e32 v138, v43, v43
	v_mul_f32_e32 v135, v41, v41
	v_fmac_f32_e32 v135, v40, v40
	v_fmac_f32_e32 v138, v42, v42
	v_add_f32_e32 v135, v135, v138
	v_mul_f32_e32 v138, v37, v37
	v_pk_add_f32 v[38:39], v[38:39], v[230:231]
	s_mov_b64 s[60:61], 0xb0000
	v_lshl_add_u64 v[238:239], v[236:237], 0, s[60:61]
	global_load_dwordx4 v[220:223], v[238:239], off offset:16
	global_load_dwordx4 v[224:227], v[238:239], off
	global_load_dwordx4 v[228:231], v[238:239], off offset:528
	global_load_dwordx4 v[232:235], v[238:239], off offset:512
	v_fmac_f32_e32 v138, v36, v36
	v_add_f32_e32 v135, v135, v138
	v_mul_f32_e32 v138, v39, v39
	v_fmac_f32_e32 v138, v38, v38
	v_add_f32_e32 v135, v138, v135
	v_add_f32_e32 v134, v134, v135
	ds_bpermute_b32 v135, v30, v134
	s_waitcnt lgkmcnt(0)
	v_add_f32_e32 v134, v134, v135
	ds_bpermute_b32 v135, v136, v134
	s_and_saveexec_b64 s[0:1], s[38:39]
	s_cbranch_execz .LBB0_342
	s_waitcnt lgkmcnt(0)
	v_add_f32_e32 v134, v134, v135
	ds_write_b32 v137, v134 offset:2304
.LBB0_342:
	s_or_b64 exec, exec, s[0:1]
	v_lshlrev_b64 v[132:133], 12, v[132:133]
	v_lshl_add_u64 v[132:133], s[6:7], 0, v[132:133]
	v_lshl_add_u64 v[132:133], v[28:29], 2, v[132:133]
	v_add_co_u32_e32 v138, vcc, 0xa0000, v132
	s_mov_b64 s[0:1], 0xa0000
	s_nop 0
	v_addc_co_u32_e32 v139, vcc, 0, v133, vcc
	s_waitcnt lgkmcnt(0)
	v_lshl_add_u64 v[134:135], v[132:133], 0, s[0:1]
	s_nop 0
	s_waitcnt vmcnt(6)
	v_pk_add_f32 v[34:35], v[34:35], v[210:211]
	v_pk_add_f32 v[32:33], v[32:33], v[208:209]
	v_mul_f32_e32 v139, v35, v35
	v_mul_f32_e32 v138, v33, v33
	v_pk_add_f32 v[24:25], v[24:25], v[204:205]
	v_fmac_f32_e32 v138, v32, v32
	v_fmac_f32_e32 v139, v34, v34
	v_add_f32_e32 v138, v138, v139
	v_mul_f32_e32 v139, v25, v25
	v_pk_add_f32 v[26:27], v[26:27], v[206:207]
	v_fmac_f32_e32 v139, v24, v24
	v_add_f32_e32 v138, v138, v139
	v_mul_f32_e32 v139, v27, v27
	v_fmac_f32_e32 v139, v26, v26
	v_add_f32_e32 v146, v139, v138
	s_waitcnt vmcnt(4)
	v_pk_add_f32 v[16:17], v[16:17], v[212:213]
	v_pk_add_f32 v[22:23], v[22:23], v[218:219]
	v_pk_add_f32 v[20:21], v[20:21], v[216:217]
	v_mul_f32_e32 v135, v23, v23
	v_mul_f32_e32 v134, v21, v21
	v_fmac_f32_e32 v134, v20, v20
	v_fmac_f32_e32 v135, v22, v22
	v_add_f32_e32 v134, v134, v135
	v_mul_f32_e32 v135, v17, v17
	v_pk_add_f32 v[18:19], v[18:19], v[214:215]
	v_fmac_f32_e32 v135, v16, v16
	v_add_f32_e32 v134, v134, v135
	v_mul_f32_e32 v135, v19, v19
	v_fmac_f32_e32 v135, v18, v18
	v_add_f32_e32 v134, v135, v134
	v_add_f32_e32 v134, v146, v134
	ds_bpermute_b32 v135, v30, v134
	s_waitcnt lgkmcnt(0)
	v_add_f32_e32 v134, v134, v135
	ds_bpermute_b32 v135, v136, v134
	s_and_saveexec_b64 s[0:1], s[38:39]
	s_cbranch_execz .LBB0_344
	s_waitcnt lgkmcnt(0)
	v_add_f32_e32 v134, v134, v135
	ds_write_b32 v137, v134 offset:2560
.LBB0_344:
	s_or_b64 exec, exec, s[0:1]
	s_mov_b64 s[0:1], 0xb0000
	v_lshl_add_u64 v[142:143], v[132:133], 0, s[0:1]
	v_add_co_u32_e32 v132, vcc, 0xb0000, v132
	s_nop 1
	v_addc_co_u32_e32 v133, vcc, 0, v133, vcc
	s_waitcnt lgkmcnt(0)
	s_nop 0
	s_waitcnt vmcnt(2)
	v_pk_add_f32 v[14:15], v[14:15], v[226:227]
	v_pk_add_f32 v[12:13], v[12:13], v[224:225]
	v_mul_f32_e32 v133, v15, v15
	v_mul_f32_e32 v132, v13, v13
	v_pk_add_f32 v[8:9], v[8:9], v[220:221]
	v_fmac_f32_e32 v132, v12, v12
	v_fmac_f32_e32 v133, v14, v14
	v_add_f32_e32 v132, v132, v133
	v_mul_f32_e32 v133, v9, v9
	v_pk_add_f32 v[10:11], v[10:11], v[222:223]
	v_fmac_f32_e32 v133, v8, v8
	v_add_f32_e32 v132, v132, v133
	v_mul_f32_e32 v133, v11, v11
	v_fmac_f32_e32 v133, v10, v10
	v_add_f32_e32 v144, v133, v132
	s_waitcnt vmcnt(0)
	v_pk_add_f32 v[0:1], v[0:1], v[228:229]
	v_pk_add_f32 v[6:7], v[6:7], v[234:235]
	v_pk_add_f32 v[4:5], v[4:5], v[232:233]
	v_mul_f32_e32 v133, v7, v7
	v_mul_f32_e32 v132, v5, v5
	v_fmac_f32_e32 v132, v4, v4
	v_fmac_f32_e32 v133, v6, v6
	v_add_f32_e32 v132, v132, v133
	v_mul_f32_e32 v133, v1, v1
	v_pk_add_f32 v[2:3], v[2:3], v[230:231]
	v_fmac_f32_e32 v133, v0, v0
	v_add_f32_e32 v132, v132, v133
	v_mul_f32_e32 v133, v3, v3
	v_fmac_f32_e32 v133, v2, v2
	v_add_f32_e32 v132, v133, v132
	v_add_f32_e32 v132, v144, v132
	ds_bpermute_b32 v30, v30, v132
	s_waitcnt lgkmcnt(0)
	v_add_f32_e32 v30, v132, v30
	ds_bpermute_b32 v132, v136, v30
	s_and_saveexec_b64 s[0:1], s[38:39]
	s_cbranch_execz .LBB0_346
	s_waitcnt lgkmcnt(0)
	v_add_f32_e32 v30, v30, v132
	ds_write_b32 v137, v30 offset:2816
